# G1 256x128 GEMM mainloop: A-fragment ds_reads software-pipelined 2 groups ahead with 3 rotating buffers and counted lgkmcnt
# speedup vs baseline: 1.7444x; 1.0097x over previous
.LBB1_1180:
	s_mul_i32 s13, s11, 0x6000
	s_add_i32 s14, s13, 0xffffa000
	s_cmp_lg_u32 s11, 0
	s_cselect_b32 s14, s14, 0xc000
	s_min_u32 s15, s12, 29
	s_lshl_b32 s96, s15, 6
	s_add_i32 s14, s14, 16
	v_lshl_add_u64 v[136:137], v[130:131], 0, s[96:97]
	s_add_i32 s15, s14, s9
	v_lshl_add_u64 v[142:143], v[136:137], 0, s[62:63]
	s_mov_b32 m0, s15
	s_waitcnt vmcnt(6)
	s_barrier
	global_load_lds_dwordx4 v[142:143], off
	v_lshl_add_u64 v[142:143], v[136:137], 0, s[60:61]
	s_add_i32 m0, s15, 0x400
	s_add_i32 s14, s14, s10
	global_load_lds_dwordx4 v[142:143], off
	v_lshl_add_u64 v[142:143], v[136:137], 0, s[16:17]
	s_add_i32 m0, s15, 0x800
	v_lshl_add_u64 v[136:137], v[136:137], 0, s[24:25]
	global_load_lds_dwordx4 v[142:143], off
	s_add_i32 m0, s15, 0xc00
	s_add_i32 s13, s13, 16
	global_load_lds_dwordx4 v[136:137], off
	v_lshl_add_u64 v[136:137], v[132:133], 0, s[96:97]
	v_lshl_add_u64 v[142:143], v[136:137], 0, s[62:63]
	s_add_i32 m0, s14, 0x4000
	v_lshl_add_u64 v[136:137], v[136:137], 0, s[60:61]
	global_load_lds_dwordx4 v[142:143], off
	s_add_i32 m0, s14, 0x4400
	s_nop 0
	global_load_lds_dwordx4 v[136:137], off
	v_add3_u32 v136, s13, v135, v134
	ds_read_b128 v[142:145], v136 offset:16384
	ds_read_b128 v[146:149], v136 offset:17408
	ds_read_b128 v[150:153], v136 offset:18432
	ds_read_b128 v[154:157], v136 offset:19456
	s_setprio 1
	v_add3_u32 v136, s13, v128, v134
	ds_read_b128 v[158:161], v136
	ds_read_b128 v[188:191], v136 offset:1024
	ds_read_b128 v[192:195], v136 offset:2048
	s_waitcnt lgkmcnt(2)
	v_mfma_f32_16x16x32_bf16 v[124:127], v[142:145], v[158:161], v[124:127]
	v_mfma_f32_16x16x32_bf16 v[120:123], v[146:149], v[158:161], v[120:123]
	v_mfma_f32_16x16x32_bf16 v[116:119], v[150:153], v[158:161], v[116:119]
	v_mfma_f32_16x16x32_bf16 v[112:115], v[154:157], v[158:161], v[112:115]
	ds_read_b128 v[158:161], v136 offset:3072
	s_waitcnt lgkmcnt(2)
	v_mfma_f32_16x16x32_bf16 v[108:111], v[142:145], v[188:191], v[108:111]
	v_mfma_f32_16x16x32_bf16 v[104:107], v[146:149], v[188:191], v[104:107]
	v_mfma_f32_16x16x32_bf16 v[100:103], v[150:153], v[188:191], v[100:103]
	v_mfma_f32_16x16x32_bf16 v[96:99], v[154:157], v[188:191], v[96:99]
	ds_read_b128 v[188:191], v136 offset:4096
	s_waitcnt lgkmcnt(2)
	v_mfma_f32_16x16x32_bf16 v[92:95], v[142:145], v[192:195], v[92:95]
	v_mfma_f32_16x16x32_bf16 v[88:91], v[146:149], v[192:195], v[88:91]
	v_mfma_f32_16x16x32_bf16 v[84:87], v[150:153], v[192:195], v[84:87]
	v_mfma_f32_16x16x32_bf16 v[80:83], v[154:157], v[192:195], v[80:83]
	ds_read_b128 v[192:195], v136 offset:5120
	s_waitcnt lgkmcnt(2)
	v_mfma_f32_16x16x32_bf16 v[76:79], v[142:145], v[158:161], v[76:79]
	v_mfma_f32_16x16x32_bf16 v[72:75], v[146:149], v[158:161], v[72:75]
	v_mfma_f32_16x16x32_bf16 v[68:71], v[150:153], v[158:161], v[68:71]
	v_mfma_f32_16x16x32_bf16 v[48:51], v[154:157], v[158:161], v[48:51]
	ds_read_b128 v[158:161], v136 offset:6144
	s_waitcnt lgkmcnt(2)
	v_mfma_f32_16x16x32_bf16 v[44:47], v[142:145], v[188:191], v[44:47]
	v_mfma_f32_16x16x32_bf16 v[40:43], v[146:149], v[188:191], v[40:43]
	v_mfma_f32_16x16x32_bf16 v[36:39], v[150:153], v[188:191], v[36:39]
	v_mfma_f32_16x16x32_bf16 v[32:35], v[154:157], v[188:191], v[32:35]
	ds_read_b128 v[188:191], v136 offset:7168
	s_waitcnt lgkmcnt(2)
	v_mfma_f32_16x16x32_bf16 v[28:31], v[142:145], v[192:195], v[28:31]
	v_mfma_f32_16x16x32_bf16 v[24:27], v[146:149], v[192:195], v[24:27]
	v_mfma_f32_16x16x32_bf16 v[20:23], v[150:153], v[192:195], v[20:23]
	v_mfma_f32_16x16x32_bf16 v[16:19], v[154:157], v[192:195], v[16:19]
	s_waitcnt lgkmcnt(1)
	v_mfma_f32_16x16x32_bf16 v[12:15], v[142:145], v[158:161], v[12:15]
	v_mfma_f32_16x16x32_bf16 v[8:11], v[146:149], v[158:161], v[8:11]
	v_mfma_f32_16x16x32_bf16 v[4:7], v[150:153], v[158:161], v[4:7]
	v_mfma_f32_16x16x32_bf16 v[0:3], v[154:157], v[158:161], v[0:3]
	s_waitcnt lgkmcnt(0)
	v_mfma_f32_16x16x32_bf16 v[60:63], v[142:145], v[188:191], v[60:63]
	v_mfma_f32_16x16x32_bf16 v[64:67], v[146:149], v[188:191], v[64:67]
	v_mfma_f32_16x16x32_bf16 v[52:55], v[150:153], v[188:191], v[52:55]
	v_mfma_f32_16x16x32_bf16 v[56:59], v[154:157], v[188:191], v[56:59]
	s_setprio 0
	s_add_i32 s13, s11, 1
	s_cmp_lg_u32 s11, 2
	s_cselect_b32 s11, s13, 0
	s_add_i32 s12, s12, 1
	s_cmp_eq_u32 s12, 32
	s_cbranch_scc0 .LBB1_1180
	s_waitcnt vmcnt(0)
	s_waitcnt vmcnt(0)
	s_barrier
	s_load_dwordx8 s[80:87], s[0:1], 0x180
	s_cmp_lt_i32 s4, 64
	v_readlane_b32 s12, v242, 9
	s_cselect_b64 s[10:11], -1, 0
	v_readlane_b32 s13, v242, 10
	s_and_b64 s[10:11], s[12:13], s[10:11]
	s_mov_b64 s[38:39], -1
	s_and_b64 vcc, exec, s[10:11]
	s_movk_i32 s12, 0x2020
	s_cbranch_vccnz .LBB1_1291
	v_or_b32_e32 v128, s6, v139
	v_add_u32_e32 v132, s8, v128
	v_lshl_or_b32 v128, v140, 2, s30
	v_or_b32_e32 v130, s7, v128
	v_lshlrev_b32_e32 v134, 5, v132
	s_movk_i32 s8, 0x1fff
	v_ashrrev_i32_e32 v135, 31, v134
	v_cmp_lt_i32_e32 vcc, s8, v130
	s_and_saveexec_b64 s[8:9], vcc
	s_xor_b64 s[40:41], exec, s[8:9]
	s_cbranch_execz .LBB1_1186
	v_cmp_gt_u32_e64 s[38:39], s12, v130
	s_and_saveexec_b64 s[42:43], s[38:39]
	s_cbranch_execz .LBB1_1185
	v_add_u32_e32 v128, 0xffffe000, v130
	v_lshl_add_u64 v[136:137], v[134:135], 2, s[78:79]
	v_lshlrev_b64 v[142:143], 2, v[128:129]
	v_lshl_add_u64 v[136:137], v[136:137], 0, v[142:143]
	v_lshl_add_u64 v[142:143], s[22:23], 0, v[142:143]
	global_load_dwordx4 v[142:145], v[142:143], off
	s_waitcnt vmcnt(0)
	v_pk_add_f32 v[144:145], v[126:127], v[144:145]
	v_pk_add_f32 v[142:143], v[124:125], v[142:143]
	global_store_dwordx4 v[136:137], v[142:145], off
